# EW2 row loop: software-prefetch next row's 12 loads into shadow VGPRs (two rows in flight), copy at loop top
# baseline (speedup 1.0000x reference)
; __device__ __forceinline__ float bf_lo(unsigned w) { return __uint_as_float(w << 16); }
; __device__ __forceinline__ float bf_hi(unsigned w) { return __uint_as_float(w & 0xffff0000u); }
; __device__ __forceinline__ f32x4 load24(const unsigned char* rowp, int blk) { const unsigned* p = (const unsigned*)(rowp + (size_t)blk * 12); const unsigned w0 = p[0], w1 = p[1], w2 = p[2];
;     return (f32x4){__uint_as_float((w0 & 0xffffffu) << 8), __uint_as_float(((w0 >> 24) | ((w1 & 0xffffu) << 8)) << 8), __uint_as_float(((w1 >> 16) | ((w2 & 0xffu) << 16)) << 8), __uint_as_float((w2 >> 8) << 8)}; }
; __device__ __forceinline__ void ew_phase(const Frame& F, const bf16_t* f, const float* gpost, float alpha, const float* hin, float* hout, const float* gpre, bf16_t* xn, ...
;     ...
;     const int it_n = prow0 >= 0 ? 8 : (T + F.NGW - 1) / F.NGW;
;     for (int it_ = 0; it_ < it_n; ++it_) {
;         const int m = prow0 >= 0 ? prow0 + F.wave * 8 + it_ : F.gw + it_ * F.NGW; if (m >= T) break;
;         const u32x2* fr = (const u32x2*)(f + (size_t)m * DM) + F.lane; const f32x4* hr = (const f32x4*)(hin + (size_t)m * DM) + F.lane;
;         f32x4 fv[4], hv[4]; float s = 0.f;
; #pragma unroll
;         for (int j = 0; j < 4; ++j) { const u32x2 w = fr[64 * j]; hv[j] = in24 ? load24(h24 + (size_t)m * (DM * 3), F.lane + 64 * j) : hr[64 * j]; fv[j] = (f32x4){bf_lo(w.x), bf_hi(w.x), bf_lo(w.y), bf_hi(w.y)};
.LBB0_809:
	v_or_b32_e32 v42, 64, v92
	v_or_b32_e32 v44, 0x80, v92
	v_or_b32_e32 v46, 0xc0, v92
	v_lshlrev_b32_e32 v38, 3, v92
	v_mov_b32_e32 v39, v1
	s_lshl_b32 s0, s11, 3
	v_readlane_b32 s1, v254, 25
	v_lshl_add_u64 v[36:37], s[58:59], 0, v[38:39]
	v_lshl_add_u64 v[38:39], s[22:23], 0, v[38:39]
	v_mul_hi_u32_u24_e32 v41, 12, v92
	v_mul_u32_u24_e32 v40, 12, v92
	v_mul_hi_u32_u24_e32 v43, 12, v42
	v_mul_u32_u24_e32 v42, 12, v42
	v_mul_hi_u32_u24_e32 v45, 12, v44
	v_mul_u32_u24_e32 v44, 12, v44
	v_mul_hi_u32_u24_e32 v47, 12, v46
	v_mul_u32_u24_e32 v46, 12, v46
	s_add_i32 s2, s1, s0
	s_mov_b32 s3, 0
	s_mov_b32 s12, s10
	v_readlane_b32 s0, v252, 11
	v_readlane_b32 s1, v252, 12
	s_and_b64 s[0:1], s[0:1], exec
	s_cselect_b32 s8, s2, s12
	s_cselect_b32 s14, 1, 0x800
	s_lshl_b32 s0, s14, 11
	s_mul_i32 s1, s14, 0xc00
	v_mov_b32_e32 v206, s14
	v_mov_b32_e32 v192, s0
	v_mov_b32_e32 v193, 0
	v_mov_b32_e32 v194, s1
	v_mov_b32_e32 v195, 0
	s_cmpk_gt_i32 s8, 0x3fff
	s_cbranch_scc1 .Lew2_pf_none
	s_ashr_i32 s9, s8, 31
	s_lshl_b64 s[0:1], s[8:9], 11
	v_lshl_add_u64 v[196:197], v[36:37], 0, s[0:1]
	s_mul_i32 s0, s8, 0xc00
	s_mul_hi_i32 s1, s8, 0xc00
	s_add_u32 s0, s25, s0
	s_addc_u32 s1, s27, s1
	v_lshl_add_u64 v[198:199], s[0:1], 0, v[40:41]
	v_lshl_add_u64 v[200:201], s[0:1], 0, v[42:43]
	v_lshl_add_u64 v[202:203], s[0:1], 0, v[44:45]
	v_lshl_add_u64 v[204:205], s[0:1], 0, v[46:47]
	global_load_dwordx2 v[168:169], v[196:197], off
	global_load_dwordx2 v[170:171], v[198:199], off
	global_load_dwordx2 v[172:173], v[198:199], off offset:4
	global_load_dwordx2 v[174:175], v[196:197], off offset:512
	global_load_dwordx2 v[176:177], v[200:201], off
	global_load_dwordx2 v[178:179], v[200:201], off offset:4
	global_load_dwordx2 v[180:181], v[196:197], off offset:1024
	global_load_dwordx2 v[182:183], v[202:203], off
	global_load_dwordx2 v[184:185], v[202:203], off offset:4
	global_load_dwordx2 v[186:187], v[196:197], off offset:1536
	global_load_dwordx2 v[188:189], v[204:205], off
	global_load_dwordx2 v[190:191], v[204:205], off offset:4
	s_waitcnt vmcnt(0)
.Lew2_pf_none:
	s_branch .LBB0_812
.LBB0_810:
	s_add_i32 s3, s3, 1
	s_addk_i32 s12, 0x800
	s_cmp_eq_u32 s3, 8
	s_cselect_b64 s[0:1], -1, 0

; __device__ __forceinline__ float bf_lo(unsigned w) { return __uint_as_float(w << 16); }
; __device__ __forceinline__ float bf_hi(unsigned w) { return __uint_as_float(w & 0xffff0000u); }
; __device__ __forceinline__ f32x4 load24(const unsigned char* rowp, int blk) { const unsigned* p = (const unsigned*)(rowp + (size_t)blk * 12); const unsigned w0 = p[0], w1 = p[1], w2 = p[2];
;     return (f32x4){__uint_as_float((w0 & 0xffffffu) << 8), __uint_as_float(((w0 >> 24) | ((w1 & 0xffffu) << 8)) << 8), __uint_as_float(((w1 >> 16) | ((w2 & 0xffu) << 16)) << 8), __uint_as_float((w2 >> 8) << 8)}; }
; __device__ __forceinline__ void ew_phase(const Frame& F, const bf16_t* f, const float* gpost, float alpha, const float* hin, float* hout, const float* gpre, bf16_t* xn, ...
;     ...
;         const int m = prow0 >= 0 ? prow0 + F.wave * 8 + it_ : F.gw + it_ * F.NGW; if (m >= T) break;
;         const u32x2* fr = (const u32x2*)(f + (size_t)m * DM) + F.lane; const f32x4* hr = (const f32x4*)(hin + (size_t)m * DM) + F.lane;
;         f32x4 fv[4], hv[4]; float s = 0.f;
; #pragma unroll
;         for (int j = 0; j < 4; ++j) { const u32x2 w = fr[64 * j]; hv[j] = in24 ? load24(h24 + (size_t)m * (DM * 3), F.lane + 64 * j) : hr[64 * j]; fv[j] = (f32x4){bf_lo(w.x), bf_hi(w.x), bf_lo(w.y), bf_hi(w.y)};
;             s += (fv[j].x * fv[j].x + fv[j].y * fv[j].y) + (fv[j].z * fv[j].z + fv[j].w * fv[j].w); }
;         const float rstd = alpha / sqrtf(wave_sum(s) * (1.f / DM) + RMS_EPS);
.LBB0_812:
	v_readlane_b32 s0, v252, 11
	s_add_i32 s8, s2, s3
	v_readlane_b32 s1, v252, 12
	s_and_b64 s[0:1], s[0:1], exec
	s_cselect_b32 s8, s8, s12
	s_cmpk_gt_i32 s8, 0x3fff
	s_mov_b64 s[0:1], -1
	s_cbranch_scc1 .LBB0_811
	s_ashr_i32 s9, s8, 31
	s_lshl_b64 s[0:1], s[8:9], 11
	s_mul_i32 s0, s8, 0xc00
	s_mul_hi_i32 s1, s8, 0xc00
	s_add_u32 s0, s25, s0
	s_addc_u32 s1, s27, s1
	v_lshl_add_u64 v[48:49], s[0:1], 0, v[40:41]
	s_waitcnt vmcnt(4)
	v_mov_b64_e32 v[56:57], v[168:169]
	v_mov_b64_e32 v[52:53], v[170:171]
	v_mov_b64_e32 v[54:55], v[172:173]
	v_mov_b64_e32 v[64:65], v[174:175]
	v_mov_b64_e32 v[62:63], v[176:177]
	v_mov_b64_e32 v[66:67], v[178:179]
	v_mov_b64_e32 v[76:77], v[180:181]
	v_mov_b64_e32 v[72:73], v[182:183]
	v_mov_b64_e32 v[74:75], v[184:185]
	v_mov_b64_e32 v[84:85], v[186:187]
	v_mov_b64_e32 v[82:83], v[188:189]
	v_mov_b64_e32 v[86:87], v[190:191]
	v_readfirstlane_b32 s14, v206
	s_add_i32 s14, s8, s14
	s_cmpk_gt_i32 s14, 0x3fff
	s_cbranch_scc1 .Lew2_pf_skip
	s_cmp_eq_u32 s3, 7
	s_cbranch_scc1 .Lew2_pf_skip
	v_lshl_add_u64 v[196:197], v[196:197], 0, v[192:193]
	v_lshl_add_u64 v[198:199], v[198:199], 0, v[194:195]
	v_lshl_add_u64 v[200:201], v[200:201], 0, v[194:195]
	v_lshl_add_u64 v[202:203], v[202:203], 0, v[194:195]
	v_lshl_add_u64 v[204:205], v[204:205], 0, v[194:195]
	global_load_dwordx2 v[168:169], v[196:197], off
	global_load_dwordx2 v[170:171], v[198:199], off
	global_load_dwordx2 v[172:173], v[198:199], off offset:4
	global_load_dwordx2 v[174:175], v[196:197], off offset:512
	global_load_dwordx2 v[176:177], v[200:201], off
	global_load_dwordx2 v[178:179], v[200:201], off offset:4
	global_load_dwordx2 v[180:181], v[196:197], off offset:1024
	global_load_dwordx2 v[182:183], v[202:203], off
	global_load_dwordx2 v[184:185], v[202:203], off offset:4
	global_load_dwordx2 v[186:187], v[196:197], off offset:1536
	global_load_dwordx2 v[188:189], v[204:205], off
	global_load_dwordx2 v[190:191], v[204:205], off offset:4
.Lew2_pf_skip:
	s_mov_b32 s14, 0xff00
	v_lshrrev_b32_e32 v53, 8, v53
	v_lshlrev_b32_e32 v51, 24, v55
	v_lshlrev_b32_e32 v54, 16, v54
	v_and_b32_e32 v53, 0xffff00, v53
	v_and_b32_sdwa v58, v52, s14 dst_sel:DWORD dst_unused:UNUSED_PAD src0_sel:WORD_1 src1_sel:DWORD
	v_lshlrev_b32_e32 v50, 8, v52
	v_or_b32_e32 v52, v51, v53
	v_or_b32_e32 v51, v54, v58
	v_and_b32_e32 v53, 0xffffff00, v55
	v_lshlrev_b32_e32 v54, 16, v56
	v_and_b32_e32 v55, 0xffff0000, v56
	v_lshlrev_b32_e32 v56, 16, v57
	v_and_b32_e32 v57, 0xffff0000, v57
	v_mul_f32_e32 v58, v57, v57
	v_pk_fma_f32 v[90:91], v[56:57], v[56:57], v[58:59] op_sel_hi:[1,1,0]
	v_lshl_add_u64 v[58:59], s[0:1], 0, v[42:43]
	v_mov_b32_e32 v98, v90
	v_lshrrev_b32_e32 v63, 8, v63
	v_lshlrev_b32_e32 v61, 24, v67
	v_lshlrev_b32_e32 v66, 16, v66
	v_and_b32_e32 v63, 0xffff00, v63
	v_and_b32_sdwa v68, v62, s14 dst_sel:DWORD dst_unused:UNUSED_PAD src0_sel:WORD_1 src1_sel:DWORD
	v_lshlrev_b32_e32 v60, 8, v62
	v_or_b32_e32 v62, v61, v63
	v_or_b32_e32 v61, v66, v68
	v_and_b32_e32 v63, 0xffffff00, v67
	v_lshlrev_b32_e32 v67, 16, v65
	v_lshlrev_b32_e32 v66, 16, v64
	v_and_b32_e32 v65, 0xffff0000, v65
	v_and_b32_e32 v64, 0xffff0000, v64
	v_pk_mul_f32 v[68:69], v[64:65], v[64:65]
	s_nop 0
	v_pk_fma_f32 v[94:95], v[66:67], v[66:67], v[68:69]
	v_lshl_add_u64 v[68:69], s[0:1], 0, v[44:45]
	v_lshl_add_u64 v[78:79], s[0:1], 0, v[46:47]
	v_pk_add_f32 v[94:95], v[94:95], v[94:95] op_sel:[0,1] op_sel_hi:[1,0]
	v_lshrrev_b32_e32 v73, 8, v73
	v_lshlrev_b32_e32 v71, 24, v75
	v_lshlrev_b32_e32 v74, 16, v74
	v_lshrrev_b32_e32 v83, 8, v83
	v_and_b32_e32 v73, 0xffff00, v73
	v_and_b32_sdwa v80, v72, s14 dst_sel:DWORD dst_unused:UNUSED_PAD src0_sel:WORD_1 src1_sel:DWORD
	v_lshlrev_b32_e32 v81, 24, v87
	v_lshlrev_b32_e32 v86, 16, v86
	v_and_b32_e32 v83, 0xffff00, v83
	v_and_b32_sdwa v88, v82, s14 dst_sel:DWORD dst_unused:UNUSED_PAD src0_sel:WORD_1 src1_sel:DWORD
	v_lshlrev_b32_e32 v70, 8, v72
	v_or_b32_e32 v72, v71, v73
	v_or_b32_e32 v71, v74, v80
	v_lshlrev_b32_e32 v80, 8, v82
	v_or_b32_e32 v82, v81, v83
	v_or_b32_e32 v81, v86, v88
	v_and_b32_e32 v83, 0xffffff00, v87
	v_and_b32_e32 v87, 0xffff0000, v84
	v_mul_f32_e32 v86, v55, v55
	v_lshlrev_b32_e32 v89, 16, v84
	v_pk_fma_f32 v[96:97], v[54:55], v[54:55], v[86:87] op_sel_hi:[1,1,0]
	v_mov_b32_e32 v99, v89
	v_mov_b32_e32 v88, v96
	v_and_b32_e32 v73, 0xffffff00, v75
	v_and_b32_e32 v75, 0xffff0000, v76
	v_mul_f32_e32 v93, v87, v87
	v_pk_add_f32 v[90:91], v[96:97], v[90:91]
	v_pk_mul_f32 v[96:97], v[88:89], v[98:99]
	v_lshlrev_b32_e32 v74, 16, v76
	v_lshlrev_b32_e32 v76, 16, v77
	v_and_b32_e32 v77, 0xffff0000, v77
	v_mov_b32_e32 v91, v97
	v_mov_b32_e32 v95, v93
	v_mul_f32_e32 v86, v75, v75
	v_lshlrev_b32_e32 v84, 16, v85
	v_and_b32_e32 v85, 0xffff0000, v85
	v_pk_add_f32 v[90:91], v[90:91], v[94:95]
	v_pk_fma_f32 v[94:95], v[74:75], v[74:75], v[86:87] op_sel_hi:[1,1,0]
	v_mul_f32_e32 v86, v77, v77
	v_mul_f32_e32 v100, v84, v84
	v_mul_f32_e32 v101, v85, v85
	v_pk_fma_f32 v[96:97], v[76:77], v[76:77], v[86:87] op_sel_hi:[1,1,0]
	v_mov_b32_e32 v95, v100
	v_mov_b32_e32 v97, v101
	v_pk_add_f32 v[94:95], v[94:95], v[96:97]
	v_and_b32_e32 v88, 64, v230
	v_pk_add_f32 v[90:91], v[90:91], v[94:95]
	v_add_u32_e32 v95, 64, v88
	v_add_f32_e32 v86, v90, v91
	s_mov_b32 s14, 0xf800000
	s_nop 1
	v_add_f32_dpp v86, v86, v86 quad_perm:[1,0,3,2] row_mask:0xf bank_mask:0xf
	s_nop 1
	v_add_f32_dpp v86, v86, v86 quad_perm:[2,3,0,1] row_mask:0xf bank_mask:0xf
	s_nop 1
	v_add_f32_dpp v86, v86, v86 row_half_mirror row_mask:0xf bank_mask:0xf
	s_nop 1
	v_add_f32_dpp v86, v86, v86 row_mirror row_mask:0xf bank_mask:0xf
	v_xor_b32_e32 v94, 16, v230
	v_cmp_lt_i32_e32 vcc, v94, v95
	s_nop 1
	v_cndmask_b32_e32 v94, v230, v94, vcc
	v_lshlrev_b32_e32 v94, 2, v94
	ds_bpermute_b32 v96, v94, v86
	s_waitcnt lgkmcnt(0)
; __device__ __forceinline__ unsigned r24(float f) { const unsigned u = __float_as_uint(f); return (u + 0x7fu + ((u >> 8) & 1u)) >> 8; }
; __device__ __forceinline__ void store24(unsigned char* rowp, int blk, f32x4 v) { const unsigned a = r24(v.x), b = r24(v.y), c = r24(v.z), d = r24(v.w); unsigned* p = (unsigned*)(rowp + (size_t)blk * 12);
;     p[0] = a | (b << 24); p[1] = (b >> 8) | (c << 16); p[2] = (c >> 16) | (d << 8); }
; __device__ __forceinline__ void ew_phase(const Frame& F, const bf16_t* f, const float* gpost, float alpha, const float* hin, float* hout, const float* gpre, bf16_t* xn, ...
;     ...
;         const float rstd = alpha / sqrtf(wave_sum(s) * (1.f / DM) + RMS_EPS);
;         float s2 = 0.f; f32x4* ho = (f32x4*)(hout + (size_t)m * DM) + F.lane;
; #pragma unroll
;         for (int j = 0; j < 4; ++j) { hv[j] = hv[j] + fv[j] * rstd * gp[j]; if (out24) store24(h24 + (size_t)m * (DM * 3), F.lane + 64 * j, hv[j]); else ho[64 * j] = hv[j]; s2 += (hv[j].x * hv[j].x + hv[j].y * hv[j].y) + (hv[j].z * hv[j].z + hv[j].w * hv[j].w); }
	v_add_f32_e32 v86, v86, v96
	v_xor_b32_e32 v96, 32, v230
	v_cmp_lt_i32_e32 vcc, v96, v95
	s_nop 1
	v_cndmask_b32_e32 v95, v230, v96, vcc
	v_lshlrev_b32_e32 v95, 2, v95
	ds_bpermute_b32 v96, v95, v86
	s_waitcnt lgkmcnt(0)
	v_add_f32_e32 v86, v86, v96
	v_fmamk_f32 v86, v86, 0x3a800000, v225
	v_cmp_gt_f32_e32 vcc, s14, v86
	v_mul_f32_e32 v96, 0x4f800000, v86
	s_nop 0
	v_cndmask_b32_e32 v86, v86, v96, vcc
	v_sqrt_f32_e32 v96, v86
	s_nop 0
	v_add_u32_e32 v97, -1, v96
	v_fma_f32 v98, -v97, v96, v86
	v_cmp_ge_f32_e64 s[0:1], 0, v98
	v_add_u32_e32 v98, 1, v96
	s_nop 0
	v_cndmask_b32_e64 v97, v96, v97, s[0:1]
	v_fma_f32 v96, -v98, v96, v86
	v_cmp_lt_f32_e64 s[0:1], 0, v96
	s_nop 1
	v_cndmask_b32_e64 v96, v97, v98, s[0:1]
	v_mul_f32_e32 v97, 0x37800000, v96
	v_cndmask_b32_e32 v96, v96, v97, vcc
	v_cmp_class_f32_e32 vcc, v86, v226
	s_nop 1
	v_cndmask_b32_e32 v86, v96, v86, vcc
	v_div_scale_f32 v96, s[0:1], v86, v86, 1.0
	v_rcp_f32_e32 v97, v96
	s_mov_b32 s0, 0x7060503
	v_fma_f32 v98, -v96, v97, 1.0
	v_fmac_f32_e32 v97, v98, v97
	v_div_scale_f32 v98, vcc, 1.0, v86, 1.0
	v_mul_f32_e32 v99, v98, v97
	v_fma_f32 v100, -v96, v99, v98
	v_fmac_f32_e32 v99, v100, v97
	v_fma_f32 v96, -v96, v99, v98
	v_div_fmas_f32 v96, v96, v97, v99
	v_div_fixup_f32 v96, v96, v86, 1.0
	v_pk_mul_f32 v[54:55], v[96:97], v[54:55] op_sel_hi:[0,1]
	v_pk_mul_f32 v[56:57], v[96:97], v[56:57] op_sel_hi:[0,1]
	v_pk_fma_f32 v[52:53], v[4:5], v[56:57], v[52:53]
	v_pk_fma_f32 v[50:51], v[2:3], v[54:55], v[50:51]
	v_bfe_u32 v57, v52, 8, 1
	v_bfe_u32 v55, v51, 8, 1
	v_bfe_u32 v54, v50, 8, 1
	v_add3_u32 v55, v51, v55, s13
	v_add3_u32 v57, v52, v57, s13
	v_bfe_u32 v97, v53, 8, 1
	v_add3_u32 v54, v50, v54, s13
	v_lshrrev_b32_e32 v56, 8, v55
	v_lshrrev_b32_e32 v86, 8, v57
	v_add3_u32 v97, v53, v97, s13
	v_alignbit_b32 v54, v56, v54, 8
	v_alignbit_b32 v55, v86, v55, 16
	v_perm_b32 v56, v97, v57, s0
	global_store_dwordx3 v[48:49], v[54:56], off
	v_mov_b32_e32 v48, v66
	v_mov_b32_e32 v49, v64
	v_mov_b32_e32 v64, v67
	v_pk_mul_f32 v[54:55], v[96:97], v[48:49] op_sel_hi:[0,1]
	v_pk_mul_f32 v[48:49], v[96:97], v[64:65] op_sel_hi:[0,1]
	v_pk_fma_f32 v[48:49], v[16:17], v[48:49], v[62:63]
	v_pk_fma_f32 v[54:55], v[14:15], v[54:55], v[60:61]
	v_bfe_u32 v61, v48, 8, 1
	v_bfe_u32 v57, v55, 8, 1
	v_bfe_u32 v56, v54, 8, 1
	v_add3_u32 v57, v55, v57, s13
	v_add3_u32 v62, v48, v61, s13
	v_bfe_u32 v63, v49, 8, 1
	v_add3_u32 v56, v54, v56, s13
	v_lshrrev_b32_e32 v60, 8, v57
	v_lshrrev_b32_e32 v61, 8, v62
	v_add3_u32 v63, v49, v63, s13
	v_alignbit_b32 v60, v60, v56, 8
	v_alignbit_b32 v61, v61, v57, 16
	v_perm_b32 v62, v63, v62, s0
	global_store_dwordx3 v[58:59], v[60:62], off
	v_pk_mul_f32 v[58:59], v[96:97], v[74:75] op_sel_hi:[0,1]
	v_pk_mul_f32 v[56:57], v[96:97], v[76:77] op_sel_hi:[0,1]
	v_pk_fma_f32 v[56:57], v[20:21], v[56:57], v[72:73]
	v_pk_fma_f32 v[58:59], v[18:19], v[58:59], v[70:71]
	v_bfe_u32 v63, v56, 8, 1
	v_bfe_u32 v61, v59, 8, 1
	v_bfe_u32 v60, v58, 8, 1
	v_add3_u32 v61, v59, v61, s13
	v_add3_u32 v63, v56, v63, s13
	v_bfe_u32 v65, v57, 8, 1
	v_add3_u32 v60, v58, v60, s13
	v_lshrrev_b32_e32 v62, 8, v61
	v_lshrrev_b32_e32 v64, 8, v63
	v_add3_u32 v65, v57, v65, s13
	v_alignbit_b32 v60, v62, v60, 8
	v_alignbit_b32 v61, v64, v61, 16
	v_perm_b32 v62, v65, v63, s0
	v_mov_b32_e32 v86, v89
	global_store_dwordx3 v[68:69], v[60:62], off
	s_and_b64 vcc, exec, s[40:41]
	s_nop 0
	v_pk_mul_f32 v[62:63], v[86:87], v[96:97] op_sel_hi:[1,0]
	v_pk_mul_f32 v[60:61], v[84:85], v[96:97] op_sel_hi:[1,0]
	v_pk_fma_f32 v[62:63], v[30:31], v[62:63], v[80:81]
	v_pk_fma_f32 v[60:61], v[32:33], v[60:61], v[82:83]
	v_bfe_u32 v65, v63, 8, 1
	v_bfe_u32 v67, v60, 8, 1
	v_bfe_u32 v64, v62, 8, 1
	v_add3_u32 v65, v63, v65, s13
	v_add3_u32 v67, v60, v67, s13
	v_bfe_u32 v69, v61, 8, 1
	v_add3_u32 v64, v62, v64, s13
	v_lshrrev_b32_e32 v66, 8, v65
	v_lshrrev_b32_e32 v68, 8, v67
	v_add3_u32 v69, v61, v69, s13
	v_alignbit_b32 v64, v66, v64, 8
	v_alignbit_b32 v65, v68, v65, 16
	v_perm_b32 v66, v69, v67, s0
	global_store_dwordx3 v[78:79], v[64:66], off
	s_cbranch_vccnz .LBB0_810
; __device__ __forceinline__ unsigned cvt_pk_bf16(float lo, float hi) { f32x2 v = {lo, hi}; bf16x2_t b = __builtin_convertvector(v, bf16x2_t); return __builtin_bit_cast(unsigned, b); }
; __device__ __forceinline__ void ew_phase(const Frame& F, const bf16_t* f, const float* gpost, float alpha, const float* hin, float* hout, const float* gpre, bf16_t* xn, ...
;     ...
;         if (gpre) {
;             const float r2 = 1.0f / sqrtf(wave_sum(s2) * (1.f / DM) + RMS_EPS);
;             u32x2* o8 = (u32x2*)(xn + (size_t)m * DM) + F.lane;
; #pragma unroll
;             for (int j = 0; j < 4; ++j) { hv[j] = hv[j] * r2 * gq[j]; u32x2 w; w.x = cvt_pk_bf16(hv[j].x, hv[j].y); w.y = cvt_pk_bf16(hv[j].z, hv[j].w); o8[64 * j] = w; }
	s_nop 0
	v_pk_mul_f32 v[64:65], v[52:53], v[52:53]
	v_pk_mul_f32 v[66:67], v[50:51], v[50:51]
	v_mov_b32_e32 v69, v65
	v_mov_b32_e32 v68, v66
	v_pk_mov_b32 v[64:65], v[66:67], v[64:65] op_sel:[1,0]
	v_pk_mul_f32 v[66:67], v[48:49], v[48:49]
	v_pk_add_f32 v[64:65], v[68:69], v[64:65]
	v_pk_mul_f32 v[68:69], v[54:55], v[54:55]
	v_pk_add_f32 v[64:65], v[64:65], v[64:65] op_sel_hi:[0,1]
	v_mov_b32_e32 v70, v68
	v_mov_b32_e32 v71, v67
	v_pk_mov_b32 v[66:67], v[68:69], v[66:67] op_sel:[1,0]
	v_mul_f32_e32 v64, v58, v58
	v_pk_add_f32 v[66:67], v[70:71], v[66:67]
	v_pk_fma_f32 v[68:69], v[58:59], v[58:59], v[64:65] op_sel_hi:[1,1,0]
	v_mul_f32_e32 v64, v56, v56
	v_pk_add_f32 v[66:67], v[66:67], v[66:67] op_sel_hi:[0,1]
	v_pk_fma_f32 v[70:71], v[56:57], v[56:57], v[64:65] op_sel_hi:[1,1,0]
	v_mul_f32_e32 v68, v62, v62
	v_mul_f32_e32 v70, v63, v63
	v_mul_f32_e32 v64, v61, v61
	v_mul_f32_e32 v66, v60, v60
	v_pk_add_f32 v[68:69], v[68:69], v[70:71]
	v_pk_add_f32 v[64:65], v[64:65], v[66:67]
	s_lshl_b64 s[8:9], s[8:9], 10
	v_pk_add_f32 v[64:65], v[68:69], v[64:65]
	s_nop 0
	v_add_f32_e32 v64, v64, v65
	s_nop 1
	v_add_f32_dpp v64, v64, v64 quad_perm:[1,0,3,2] row_mask:0xf bank_mask:0xf
	s_nop 1
	v_add_f32_dpp v64, v64, v64 quad_perm:[2,3,0,1] row_mask:0xf bank_mask:0xf
	s_nop 1
	v_add_f32_dpp v64, v64, v64 row_half_mirror row_mask:0xf bank_mask:0xf
	s_nop 1
	v_add_f32_dpp v64, v64, v64 row_mirror row_mask:0xf bank_mask:0xf
	ds_bpermute_b32 v65, v94, v64
	s_waitcnt lgkmcnt(0)
	v_add_f32_e32 v64, v64, v65
	ds_bpermute_b32 v65, v95, v64
	s_waitcnt lgkmcnt(0)
	v_add_f32_e32 v64, v64, v65
	v_fmamk_f32 v64, v64, 0x3a800000, v225
	v_mul_f32_e32 v65, 0x4f800000, v64
	v_cmp_gt_f32_e32 vcc, s14, v64
	s_nop 1
	v_cndmask_b32_e32 v64, v64, v65, vcc
	v_sqrt_f32_e32 v65, v64
	s_nop 0
	v_add_u32_e32 v66, -1, v65
	v_add_u32_e32 v67, 1, v65
	v_fma_f32 v68, -v66, v65, v64
	v_fma_f32 v69, -v67, v65, v64
	v_cmp_ge_f32_e64 s[0:1], 0, v68
	s_nop 1
	v_cndmask_b32_e64 v65, v65, v66, s[0:1]
	v_cmp_lt_f32_e64 s[0:1], 0, v69
	s_nop 1
	v_cndmask_b32_e64 v65, v65, v67, s[0:1]
	v_mul_f32_e32 v66, 0x37800000, v65
	v_cndmask_b32_e32 v65, v65, v66, vcc
	v_cmp_class_f32_e32 vcc, v64, v226
	s_nop 1
	v_cndmask_b32_e32 v66, v65, v64, vcc
	v_div_scale_f32 v67, s[0:1], v66, v66, 1.0
	v_rcp_f32_e32 v68, v67
	v_div_scale_f32 v69, vcc, 1.0, v66, 1.0
	v_lshl_add_u64 v[64:65], s[8:9], 1, v[38:39]
	v_fma_f32 v70, -v67, v68, 1.0
	v_fmac_f32_e32 v68, v70, v68
	v_mul_f32_e32 v70, v69, v68
	v_fma_f32 v71, -v67, v70, v69
	v_fmac_f32_e32 v70, v71, v68
	v_fma_f32 v67, -v67, v70, v69
	v_div_fmas_f32 v67, v67, v68, v70
	v_div_fixup_f32 v66, v67, v66, 1.0
	v_pk_mul_f32 v[50:51], v[50:51], v[66:67] op_sel_hi:[1,0]
	v_pk_mul_f32 v[52:53], v[52:53], v[66:67] op_sel_hi:[1,0]
	v_pk_mul_f32 v[50:51], v[10:11], v[50:51]
	v_pk_mul_f32 v[52:53], v[12:13], v[52:53]
	v_cvt_pk_bf16_f32 v50, v50, v51
	v_cvt_pk_bf16_f32 v51, v52, v53
	global_store_dwordx2 v[64:65], v[50:51], off
	v_pk_mul_f32 v[50:51], v[54:55], v[66:67] op_sel_hi:[1,0]
	v_pk_mul_f32 v[48:49], v[48:49], v[66:67] op_sel_hi:[1,0]
	v_pk_mul_f32 v[50:51], v[6:7], v[50:51]
	v_pk_mul_f32 v[48:49], v[8:9], v[48:49]
	v_cvt_pk_bf16_f32 v50, v50, v51
	v_cvt_pk_bf16_f32 v51, v48, v49
	global_store_dwordx2 v[64:65], v[50:51], off offset:512
	v_pk_mul_f32 v[48:49], v[58:59], v[66:67] op_sel_hi:[1,0]
	v_pk_mul_f32 v[50:51], v[56:57], v[66:67] op_sel_hi:[1,0]
	v_pk_mul_f32 v[48:49], v[26:27], v[48:49]
	v_pk_mul_f32 v[50:51], v[28:29], v[50:51]
	v_cvt_pk_bf16_f32 v48, v48, v49
	v_cvt_pk_bf16_f32 v49, v50, v51
	global_store_dwordx2 v[64:65], v[48:49], off offset:1024
	v_pk_mul_f32 v[48:49], v[62:63], v[66:67] op_sel_hi:[1,0]
	v_pk_mul_f32 v[50:51], v[60:61], v[66:67] op_sel_hi:[1,0]
	v_pk_mul_f32 v[48:49], v[22:23], v[48:49]
	v_pk_mul_f32 v[50:51], v[24:25], v[50:51]
	v_cvt_pk_bf16_f32 v48, v48, v49
	v_cvt_pk_bf16_f32 v49, v50, v51
	global_store_dwordx2 v[64:65], v[48:49], off offset:1536
	s_branch .LBB0_810
